# v26 + w_out/FFN-down epilogue access shape: accumulator quads exchanged across lanes (permlane16_swap + permlane32_swap) so each 16-byte load/store instruction covers 64 contiguous bytes per row
# baseline (speedup 1.0000x reference)
; template <class Epi>
; __device__ __forceinline__ void gemm_phase(LAS unsigned char* lds, const Gemm g, const Epi& E) {
;     ...
;           for (int bj = 0; bj < 2; ++bj)
;           { E.st2(cur.w, cur.pm * BM + ai * HALF + wr * 64 + m * 16 + fr, cur.pn * BM + bj * HALF + wc * 32 + 8 * fq, acc[ai][bj][m][0], acc[ai][bj][m][1]); if (bj == 1 && (m & 1)) asm volatile("" ::: "memory"); }
.Lepi5:
	v_lshlrev_b32_e32 v176, 12, v150
	v_lshl_add_u32 v176, v148, 2, v176
	v_and_b32_e32 v177, 24, v174
	v_lshlrev_b32_e32 v177, 1, v177
	v_sub_u32_e32 v176, v176, v177
	v_add_u32_e32 v177, 0x10000, v176
	v_add_u32_e32 v178, 0x20000, v176
	v_add_u32_e32 v179, 0x30000, v176
	v_add_u32_e32 v180, 0x80000, v176
	v_add_u32_e32 v181, 0x90000, v176
	v_add_u32_e32 v182, 0xa0000, v176
	v_add_u32_e32 v183, 0xb0000, v176
	global_load_dwordx4 v[184:187], v176, s[24:25] nt
	global_load_dwordx4 v[188:191], v176, s[24:25] offset:64 nt
	global_load_dwordx4 v[192:195], v176, s[24:25] offset:512 nt
	global_load_dwordx4 v[196:199], v176, s[24:25] offset:576 nt
	global_load_dwordx4 v[200:203], v177, s[24:25] nt
	global_load_dwordx4 v[204:207], v177, s[24:25] offset:64 nt
	global_load_dwordx4 v[208:211], v177, s[24:25] offset:512 nt
	global_load_dwordx4 v[212:215], v177, s[24:25] offset:576 nt
	global_load_dwordx4 v[216:219], v178, s[24:25] nt
	global_load_dwordx4 v[220:223], v178, s[24:25] offset:64 nt
	global_load_dwordx4 v[152:155], v178, s[24:25] offset:512 nt
	global_load_dwordx4 v[156:159], v178, s[24:25] offset:576 nt
	global_load_dwordx4 v[160:163], v179, s[24:25] nt
	global_load_dwordx4 v[164:167], v179, s[24:25] offset:64 nt
	global_load_dwordx4 v[168:171], v179, s[24:25] offset:512 nt
	global_load_dwordx4 v[128:131], v179, s[24:25] offset:576 nt
	v_permlane16_swap_b32_e32 v124, v120
	v_permlane16_swap_b32_e32 v125, v121
	v_permlane16_swap_b32_e32 v126, v122
	v_permlane16_swap_b32_e32 v127, v123
	v_permlane32_swap_b32_e32 v124, v120
	v_permlane32_swap_b32_e32 v125, v121
	v_permlane32_swap_b32_e32 v126, v122
	v_permlane32_swap_b32_e32 v127, v123
	s_nop 1
	s_waitcnt vmcnt(14)
	v_pk_add_f32 v[186:187], v[126:127], v[186:187]
	v_pk_add_f32 v[184:185], v[124:125], v[184:185]
	v_pk_add_f32 v[190:191], v[122:123], v[190:191]
	v_pk_add_f32 v[188:189], v[120:121], v[188:189]
	global_store_dwordx4 v176, v[184:187], s[58:59]
	global_store_dwordx4 v176, v[188:191], s[58:59] offset:64
	global_load_dwordx4 v[124:127], v180, s[24:25] nt
	global_load_dwordx4 v[120:123], v180, s[24:25] offset:64 nt
	v_permlane16_swap_b32_e32 v116, v112
	v_permlane16_swap_b32_e32 v117, v113
	v_permlane16_swap_b32_e32 v118, v114
	v_permlane16_swap_b32_e32 v119, v115
	v_permlane32_swap_b32_e32 v116, v112
	v_permlane32_swap_b32_e32 v117, v113
	v_permlane32_swap_b32_e32 v118, v114
	v_permlane32_swap_b32_e32 v119, v115
	s_nop 1
	s_waitcnt vmcnt(16)
	v_pk_add_f32 v[194:195], v[118:119], v[194:195]
	v_pk_add_f32 v[192:193], v[116:117], v[192:193]
	v_pk_add_f32 v[198:199], v[114:115], v[198:199]
	v_pk_add_f32 v[196:197], v[112:113], v[196:197]
	global_store_dwordx4 v176, v[192:195], s[58:59] offset:512
	global_store_dwordx4 v176, v[196:199], s[58:59] offset:576
	global_load_dwordx4 v[116:119], v180, s[24:25] offset:512 nt
	global_load_dwordx4 v[112:115], v180, s[24:25] offset:576 nt
	v_permlane16_swap_b32_e32 v108, v104
	v_permlane16_swap_b32_e32 v109, v105
	v_permlane16_swap_b32_e32 v110, v106
	v_permlane16_swap_b32_e32 v111, v107
	v_permlane32_swap_b32_e32 v108, v104
	v_permlane32_swap_b32_e32 v109, v105
	v_permlane32_swap_b32_e32 v110, v106
	v_permlane32_swap_b32_e32 v111, v107
	s_nop 1
	s_waitcnt vmcnt(18)
	v_pk_add_f32 v[202:203], v[110:111], v[202:203]
	v_pk_add_f32 v[200:201], v[108:109], v[200:201]
	v_pk_add_f32 v[206:207], v[106:107], v[206:207]
	v_pk_add_f32 v[204:205], v[104:105], v[204:205]
	global_store_dwordx4 v177, v[200:203], s[58:59]
	global_store_dwordx4 v177, v[204:207], s[58:59] offset:64
	global_load_dwordx4 v[108:111], v181, s[24:25] nt
	global_load_dwordx4 v[104:107], v181, s[24:25] offset:64 nt
	v_permlane16_swap_b32_e32 v100, v96
	v_permlane16_swap_b32_e32 v101, v97
	v_permlane16_swap_b32_e32 v102, v98
	v_permlane16_swap_b32_e32 v103, v99
	v_permlane32_swap_b32_e32 v100, v96
	v_permlane32_swap_b32_e32 v101, v97
	v_permlane32_swap_b32_e32 v102, v98
	v_permlane32_swap_b32_e32 v103, v99
	s_nop 1
	s_waitcnt vmcnt(20)
	v_pk_add_f32 v[210:211], v[102:103], v[210:211]
	v_pk_add_f32 v[208:209], v[100:101], v[208:209]
	v_pk_add_f32 v[214:215], v[98:99], v[214:215]
	v_pk_add_f32 v[212:213], v[96:97], v[212:213]
	global_store_dwordx4 v177, v[208:211], s[58:59] offset:512
	global_store_dwordx4 v177, v[212:215], s[58:59] offset:576
	global_load_dwordx4 v[100:103], v181, s[24:25] offset:512 nt
	global_load_dwordx4 v[96:99], v181, s[24:25] offset:576 nt
	v_permlane16_swap_b32_e32 v92, v88
	v_permlane16_swap_b32_e32 v93, v89
	v_permlane16_swap_b32_e32 v94, v90
	v_permlane16_swap_b32_e32 v95, v91
	v_permlane32_swap_b32_e32 v92, v88
	v_permlane32_swap_b32_e32 v93, v89
	v_permlane32_swap_b32_e32 v94, v90
	v_permlane32_swap_b32_e32 v95, v91
	s_nop 1
	s_waitcnt vmcnt(22)
	v_pk_add_f32 v[218:219], v[94:95], v[218:219]
	v_pk_add_f32 v[216:217], v[92:93], v[216:217]
	v_pk_add_f32 v[222:223], v[90:91], v[222:223]
	v_pk_add_f32 v[220:221], v[88:89], v[220:221]
	global_store_dwordx4 v178, v[216:219], s[58:59]
	global_store_dwordx4 v178, v[220:223], s[58:59] offset:64
	global_load_dwordx4 v[92:95], v182, s[24:25] nt
	global_load_dwordx4 v[88:91], v182, s[24:25] offset:64 nt
	v_permlane16_swap_b32_e32 v84, v80
	v_permlane16_swap_b32_e32 v85, v81
	v_permlane16_swap_b32_e32 v86, v82
	v_permlane16_swap_b32_e32 v87, v83
	v_permlane32_swap_b32_e32 v84, v80
	v_permlane32_swap_b32_e32 v85, v81
	v_permlane32_swap_b32_e32 v86, v82
	v_permlane32_swap_b32_e32 v87, v83
	s_nop 1
	s_waitcnt vmcnt(24)
; template <class Epi>
; __device__ __forceinline__ void gemm_phase(LAS unsigned char* lds, const Gemm g, const Epi& E) {
;     ...
;           for (int bj = 0; bj < 2; ++bj)
;           { E.st2(cur.w, cur.pm * BM + ai * HALF + wr * 64 + m * 16 + fr, cur.pn * BM + bj * HALF + wc * 32 + 8 * fq, acc[ai][bj][m][0], acc[ai][bj][m][1]); if (bj == 1 && (m & 1)) asm volatile("" ::: "memory"); }
	v_pk_add_f32 v[154:155], v[86:87], v[154:155]
	v_pk_add_f32 v[152:153], v[84:85], v[152:153]
	v_pk_add_f32 v[158:159], v[82:83], v[158:159]
	v_pk_add_f32 v[156:157], v[80:81], v[156:157]
	global_store_dwordx4 v178, v[152:155], s[58:59] offset:512
	global_store_dwordx4 v178, v[156:159], s[58:59] offset:576
	global_load_dwordx4 v[84:87], v182, s[24:25] offset:512 nt
	global_load_dwordx4 v[80:83], v182, s[24:25] offset:576 nt
	v_permlane16_swap_b32_e32 v76, v72
	v_permlane16_swap_b32_e32 v77, v73
	v_permlane16_swap_b32_e32 v78, v74
	v_permlane16_swap_b32_e32 v79, v75
	v_permlane32_swap_b32_e32 v76, v72
	v_permlane32_swap_b32_e32 v77, v73
	v_permlane32_swap_b32_e32 v78, v74
	v_permlane32_swap_b32_e32 v79, v75
	s_nop 1
	s_waitcnt vmcnt(26)
	v_pk_add_f32 v[162:163], v[78:79], v[162:163]
	v_pk_add_f32 v[160:161], v[76:77], v[160:161]
	v_pk_add_f32 v[166:167], v[74:75], v[166:167]
	v_pk_add_f32 v[164:165], v[72:73], v[164:165]
	global_store_dwordx4 v179, v[160:163], s[58:59]
	global_store_dwordx4 v179, v[164:167], s[58:59] offset:64
	global_load_dwordx4 v[76:79], v183, s[24:25] nt
	global_load_dwordx4 v[72:75], v183, s[24:25] offset:64 nt
	v_permlane16_swap_b32_e32 v68, v64
	v_permlane16_swap_b32_e32 v69, v65
	v_permlane16_swap_b32_e32 v70, v66
	v_permlane16_swap_b32_e32 v71, v67
	v_permlane32_swap_b32_e32 v68, v64
	v_permlane32_swap_b32_e32 v69, v65
	v_permlane32_swap_b32_e32 v70, v66
	v_permlane32_swap_b32_e32 v71, v67
	s_nop 1
	s_waitcnt vmcnt(28)
	v_pk_add_f32 v[170:171], v[70:71], v[170:171]
	v_pk_add_f32 v[168:169], v[68:69], v[168:169]
	v_pk_add_f32 v[130:131], v[66:67], v[130:131]
	v_pk_add_f32 v[128:129], v[64:65], v[128:129]
	global_store_dwordx4 v179, v[168:171], s[58:59] offset:512
	global_store_dwordx4 v179, v[128:131], s[58:59] offset:576
	global_load_dwordx4 v[68:71], v183, s[24:25] offset:512 nt
	global_load_dwordx4 v[64:67], v183, s[24:25] offset:576 nt
	v_permlane16_swap_b32_e32 v60, v56
	v_permlane16_swap_b32_e32 v61, v57
	v_permlane16_swap_b32_e32 v62, v58
	v_permlane16_swap_b32_e32 v63, v59
	v_permlane32_swap_b32_e32 v60, v56
	v_permlane32_swap_b32_e32 v61, v57
	v_permlane32_swap_b32_e32 v62, v58
	v_permlane32_swap_b32_e32 v63, v59
	s_nop 1
	s_waitcnt vmcnt(28)
	v_pk_add_f32 v[126:127], v[62:63], v[126:127]
	v_pk_add_f32 v[124:125], v[60:61], v[124:125]
	v_pk_add_f32 v[122:123], v[58:59], v[122:123]
	v_pk_add_f32 v[120:121], v[56:57], v[120:121]
	global_store_dwordx4 v180, v[124:127], s[58:59]
	global_store_dwordx4 v180, v[120:123], s[58:59] offset:64
	v_permlane16_swap_b32_e32 v52, v48
	v_permlane16_swap_b32_e32 v53, v49
	v_permlane16_swap_b32_e32 v54, v50
	v_permlane16_swap_b32_e32 v55, v51
	v_permlane32_swap_b32_e32 v52, v48
	v_permlane32_swap_b32_e32 v53, v49
	v_permlane32_swap_b32_e32 v54, v50
	v_permlane32_swap_b32_e32 v55, v51
	s_nop 1
	s_waitcnt vmcnt(26)
	v_pk_add_f32 v[118:119], v[54:55], v[118:119]
	v_pk_add_f32 v[116:117], v[52:53], v[116:117]
	v_pk_add_f32 v[114:115], v[50:51], v[114:115]
	v_pk_add_f32 v[112:113], v[48:49], v[112:113]
	global_store_dwordx4 v180, v[116:119], s[58:59] offset:512
	global_store_dwordx4 v180, v[112:115], s[58:59] offset:576
	v_permlane16_swap_b32_e32 v44, v40
	v_permlane16_swap_b32_e32 v45, v41
	v_permlane16_swap_b32_e32 v46, v42
	v_permlane16_swap_b32_e32 v47, v43
	v_permlane32_swap_b32_e32 v44, v40
	v_permlane32_swap_b32_e32 v45, v41
	v_permlane32_swap_b32_e32 v46, v42
	v_permlane32_swap_b32_e32 v47, v43
	s_nop 1
	s_waitcnt vmcnt(24)
	v_pk_add_f32 v[110:111], v[46:47], v[110:111]
	v_pk_add_f32 v[108:109], v[44:45], v[108:109]
	v_pk_add_f32 v[106:107], v[42:43], v[106:107]
	v_pk_add_f32 v[104:105], v[40:41], v[104:105]
	global_store_dwordx4 v181, v[108:111], s[58:59]
	global_store_dwordx4 v181, v[104:107], s[58:59] offset:64
	v_permlane16_swap_b32_e32 v36, v32
	v_permlane16_swap_b32_e32 v37, v33
	v_permlane16_swap_b32_e32 v38, v34
	v_permlane16_swap_b32_e32 v39, v35
	v_permlane32_swap_b32_e32 v36, v32
	v_permlane32_swap_b32_e32 v37, v33
	v_permlane32_swap_b32_e32 v38, v34
	v_permlane32_swap_b32_e32 v39, v35
	s_nop 1
	s_waitcnt vmcnt(22)
	v_pk_add_f32 v[102:103], v[38:39], v[102:103]
	v_pk_add_f32 v[100:101], v[36:37], v[100:101]
	v_pk_add_f32 v[98:99], v[34:35], v[98:99]
	v_pk_add_f32 v[96:97], v[32:33], v[96:97]
	global_store_dwordx4 v181, v[100:103], s[58:59] offset:512
	global_store_dwordx4 v181, v[96:99], s[58:59] offset:576
	v_permlane16_swap_b32_e32 v28, v24
	v_permlane16_swap_b32_e32 v29, v25
	v_permlane16_swap_b32_e32 v30, v26
	v_permlane16_swap_b32_e32 v31, v27
	v_permlane32_swap_b32_e32 v28, v24
	v_permlane32_swap_b32_e32 v29, v25
	v_permlane32_swap_b32_e32 v30, v26
	v_permlane32_swap_b32_e32 v31, v27
	s_nop 1
	s_waitcnt vmcnt(20)
	v_pk_add_f32 v[94:95], v[30:31], v[94:95]
	v_pk_add_f32 v[92:93], v[28:29], v[92:93]
	v_pk_add_f32 v[90:91], v[26:27], v[90:91]
	v_pk_add_f32 v[88:89], v[24:25], v[88:89]
	global_store_dwordx4 v182, v[92:95], s[58:59]
	global_store_dwordx4 v182, v[88:91], s[58:59] offset:64
	v_permlane16_swap_b32_e32 v20, v16
	v_permlane16_swap_b32_e32 v21, v17
	v_permlane16_swap_b32_e32 v22, v18
	v_permlane16_swap_b32_e32 v23, v19
	v_permlane32_swap_b32_e32 v20, v16
	v_permlane32_swap_b32_e32 v21, v17
	v_permlane32_swap_b32_e32 v22, v18
	v_permlane32_swap_b32_e32 v23, v19
	s_nop 1
	s_waitcnt vmcnt(18)
	v_pk_add_f32 v[86:87], v[22:23], v[86:87]
	v_pk_add_f32 v[84:85], v[20:21], v[84:85]
	v_pk_add_f32 v[82:83], v[18:19], v[82:83]
	v_pk_add_f32 v[80:81], v[16:17], v[80:81]
	global_store_dwordx4 v182, v[84:87], s[58:59] offset:512
	global_store_dwordx4 v182, v[80:83], s[58:59] offset:576
	v_permlane16_swap_b32_e32 v12, v8
	v_permlane16_swap_b32_e32 v13, v9
	v_permlane16_swap_b32_e32 v14, v10
	v_permlane16_swap_b32_e32 v15, v11
	v_permlane32_swap_b32_e32 v12, v8
	v_permlane32_swap_b32_e32 v13, v9
	v_permlane32_swap_b32_e32 v14, v10
	v_permlane32_swap_b32_e32 v15, v11
	s_nop 1
	s_waitcnt vmcnt(16)
	v_pk_add_f32 v[78:79], v[14:15], v[78:79]
	v_pk_add_f32 v[76:77], v[12:13], v[76:77]
	v_pk_add_f32 v[74:75], v[10:11], v[74:75]
	v_pk_add_f32 v[72:73], v[8:9], v[72:73]
	global_store_dwordx4 v183, v[76:79], s[58:59]
	global_store_dwordx4 v183, v[72:75], s[58:59] offset:64
	v_permlane16_swap_b32_e32 v4, v0
	v_permlane16_swap_b32_e32 v5, v1
	v_permlane16_swap_b32_e32 v6, v2
	v_permlane16_swap_b32_e32 v7, v3
	v_permlane32_swap_b32_e32 v4, v0
	v_permlane32_swap_b32_e32 v5, v1
	v_permlane32_swap_b32_e32 v6, v2
	v_permlane32_swap_b32_e32 v7, v3
	s_nop 1
	s_waitcnt vmcnt(14)
	v_pk_add_f32 v[70:71], v[6:7], v[70:71]
	v_pk_add_f32 v[68:69], v[4:5], v[68:69]
	v_pk_add_f32 v[66:67], v[2:3], v[66:67]
	v_pk_add_f32 v[64:65], v[0:1], v[64:65]
	global_store_dwordx4 v183, v[68:71], s[58:59] offset:512
	global_store_dwordx4 v183, v[64:67], s[58:59] offset:576
	s_branch .LBB0_567
; template <class Epi>
; __device__ __forceinline__ void gemm_phase(LAS unsigned char* lds, const Gemm g, const Epi& E) {
;     ...
;           for (int bj = 0; bj < 2; ++bj)
;           { E.st2(cur.w, cur.pm * BM + ai * HALF + wr * 64 + m * 16 + fr, cur.pn * BM + bj * HALF + wc * 32 + 8 * fq, acc[ai][bj][m][0], acc[ai][bj][m][1]); if (bj == 1 && (m & 1)) asm volatile("" ::: "memory"); }
.Lepi7:
	v_lshlrev_b32_e32 v176, 12, v150
	v_lshl_add_u32 v176, v148, 2, v176
	v_and_b32_e32 v177, 24, v174
	v_lshlrev_b32_e32 v177, 1, v177
	v_sub_u32_e32 v176, v176, v177
	v_add_u32_e32 v177, 0x10000, v176
	v_add_u32_e32 v178, 0x20000, v176
	v_add_u32_e32 v179, 0x30000, v176
	v_add_u32_e32 v180, 0x80000, v176
	v_add_u32_e32 v181, 0x90000, v176
	v_add_u32_e32 v182, 0xa0000, v176
	v_add_u32_e32 v183, 0xb0000, v176
	global_load_dwordx4 v[184:187], v176, s[58:59] nt
	global_load_dwordx4 v[188:191], v176, s[58:59] offset:64 nt
	global_load_dwordx4 v[192:195], v176, s[58:59] offset:512 nt
	global_load_dwordx4 v[196:199], v176, s[58:59] offset:576 nt
	global_load_dwordx4 v[200:203], v177, s[58:59] nt
	global_load_dwordx4 v[204:207], v177, s[58:59] offset:64 nt
	global_load_dwordx4 v[208:211], v177, s[58:59] offset:512 nt
	global_load_dwordx4 v[212:215], v177, s[58:59] offset:576 nt
	global_load_dwordx4 v[216:219], v178, s[58:59] nt
	global_load_dwordx4 v[220:223], v178, s[58:59] offset:64 nt
	global_load_dwordx4 v[152:155], v178, s[58:59] offset:512 nt
	global_load_dwordx4 v[156:159], v178, s[58:59] offset:576 nt
	global_load_dwordx4 v[160:163], v179, s[58:59] nt
	global_load_dwordx4 v[164:167], v179, s[58:59] offset:64 nt
	global_load_dwordx4 v[168:171], v179, s[58:59] offset:512 nt
	global_load_dwordx4 v[128:131], v179, s[58:59] offset:576 nt
	v_permlane16_swap_b32_e32 v124, v120
	v_permlane16_swap_b32_e32 v125, v121
	v_permlane16_swap_b32_e32 v126, v122
	v_permlane16_swap_b32_e32 v127, v123
	v_permlane32_swap_b32_e32 v124, v120
	v_permlane32_swap_b32_e32 v125, v121
	v_permlane32_swap_b32_e32 v126, v122
	v_permlane32_swap_b32_e32 v127, v123
	s_nop 1
	s_waitcnt vmcnt(14)
	v_pk_add_f32 v[186:187], v[126:127], v[186:187]
	v_pk_add_f32 v[184:185], v[124:125], v[184:185]
	v_pk_add_f32 v[190:191], v[122:123], v[190:191]
	v_pk_add_f32 v[188:189], v[120:121], v[188:189]
	global_store_dwordx4 v176, v[184:187], s[58:59] nt
	global_store_dwordx4 v176, v[188:191], s[58:59] offset:64 nt
	global_load_dwordx4 v[124:127], v180, s[58:59] nt
	global_load_dwordx4 v[120:123], v180, s[58:59] offset:64 nt
	v_permlane16_swap_b32_e32 v116, v112
	v_permlane16_swap_b32_e32 v117, v113
	v_permlane16_swap_b32_e32 v118, v114
	v_permlane16_swap_b32_e32 v119, v115
	v_permlane32_swap_b32_e32 v116, v112
	v_permlane32_swap_b32_e32 v117, v113
	v_permlane32_swap_b32_e32 v118, v114
	v_permlane32_swap_b32_e32 v119, v115
	s_nop 1
	s_waitcnt vmcnt(16)
	v_pk_add_f32 v[194:195], v[118:119], v[194:195]
	v_pk_add_f32 v[192:193], v[116:117], v[192:193]
	v_pk_add_f32 v[198:199], v[114:115], v[198:199]
	v_pk_add_f32 v[196:197], v[112:113], v[196:197]
	global_store_dwordx4 v176, v[192:195], s[58:59] offset:512 nt
	global_store_dwordx4 v176, v[196:199], s[58:59] offset:576 nt
	global_load_dwordx4 v[116:119], v180, s[58:59] offset:512 nt
	global_load_dwordx4 v[112:115], v180, s[58:59] offset:576 nt
	v_permlane16_swap_b32_e32 v108, v104
	v_permlane16_swap_b32_e32 v109, v105
	v_permlane16_swap_b32_e32 v110, v106
	v_permlane16_swap_b32_e32 v111, v107
	v_permlane32_swap_b32_e32 v108, v104
	v_permlane32_swap_b32_e32 v109, v105
	v_permlane32_swap_b32_e32 v110, v106
	v_permlane32_swap_b32_e32 v111, v107
	s_nop 1
	s_waitcnt vmcnt(18)
	v_pk_add_f32 v[202:203], v[110:111], v[202:203]
	v_pk_add_f32 v[200:201], v[108:109], v[200:201]
	v_pk_add_f32 v[206:207], v[106:107], v[206:207]
	v_pk_add_f32 v[204:205], v[104:105], v[204:205]
	global_store_dwordx4 v177, v[200:203], s[58:59] nt
	global_store_dwordx4 v177, v[204:207], s[58:59] offset:64 nt
	global_load_dwordx4 v[108:111], v181, s[58:59] nt
	global_load_dwordx4 v[104:107], v181, s[58:59] offset:64 nt
	v_permlane16_swap_b32_e32 v100, v96
	v_permlane16_swap_b32_e32 v101, v97
	v_permlane16_swap_b32_e32 v102, v98
	v_permlane16_swap_b32_e32 v103, v99
	v_permlane32_swap_b32_e32 v100, v96
	v_permlane32_swap_b32_e32 v101, v97
	v_permlane32_swap_b32_e32 v102, v98
	v_permlane32_swap_b32_e32 v103, v99
	s_nop 1
	s_waitcnt vmcnt(20)
	v_pk_add_f32 v[210:211], v[102:103], v[210:211]
	v_pk_add_f32 v[208:209], v[100:101], v[208:209]
	v_pk_add_f32 v[214:215], v[98:99], v[214:215]
	v_pk_add_f32 v[212:213], v[96:97], v[212:213]
	global_store_dwordx4 v177, v[208:211], s[58:59] offset:512 nt
	global_store_dwordx4 v177, v[212:215], s[58:59] offset:576 nt
	global_load_dwordx4 v[100:103], v181, s[58:59] offset:512 nt
	global_load_dwordx4 v[96:99], v181, s[58:59] offset:576 nt
	v_permlane16_swap_b32_e32 v92, v88
	v_permlane16_swap_b32_e32 v93, v89
	v_permlane16_swap_b32_e32 v94, v90
	v_permlane16_swap_b32_e32 v95, v91
	v_permlane32_swap_b32_e32 v92, v88
	v_permlane32_swap_b32_e32 v93, v89
	v_permlane32_swap_b32_e32 v94, v90
	v_permlane32_swap_b32_e32 v95, v91
	s_nop 1
	s_waitcnt vmcnt(22)
	v_pk_add_f32 v[218:219], v[94:95], v[218:219]
	v_pk_add_f32 v[216:217], v[92:93], v[216:217]
	v_pk_add_f32 v[222:223], v[90:91], v[222:223]
	v_pk_add_f32 v[220:221], v[88:89], v[220:221]
	global_store_dwordx4 v178, v[216:219], s[58:59] nt
	global_store_dwordx4 v178, v[220:223], s[58:59] offset:64 nt
	global_load_dwordx4 v[92:95], v182, s[58:59] nt
	global_load_dwordx4 v[88:91], v182, s[58:59] offset:64 nt
	v_permlane16_swap_b32_e32 v84, v80
	v_permlane16_swap_b32_e32 v85, v81
	v_permlane16_swap_b32_e32 v86, v82
	v_permlane16_swap_b32_e32 v87, v83
	v_permlane32_swap_b32_e32 v84, v80
	v_permlane32_swap_b32_e32 v85, v81
	v_permlane32_swap_b32_e32 v86, v82
	v_permlane32_swap_b32_e32 v87, v83
	s_nop 1
	s_waitcnt vmcnt(24)
; template <class Epi>
; __device__ __forceinline__ void gemm_phase(LAS unsigned char* lds, const Gemm g, const Epi& E) {
;     ...
;           for (int bj = 0; bj < 2; ++bj)
;           { E.st2(cur.w, cur.pm * BM + ai * HALF + wr * 64 + m * 16 + fr, cur.pn * BM + bj * HALF + wc * 32 + 8 * fq, acc[ai][bj][m][0], acc[ai][bj][m][1]); if (bj == 1 && (m & 1)) asm volatile("" ::: "memory"); }
	v_pk_add_f32 v[154:155], v[86:87], v[154:155]
	v_pk_add_f32 v[152:153], v[84:85], v[152:153]
	v_pk_add_f32 v[158:159], v[82:83], v[158:159]
	v_pk_add_f32 v[156:157], v[80:81], v[156:157]
	global_store_dwordx4 v178, v[152:155], s[58:59] offset:512 nt
	global_store_dwordx4 v178, v[156:159], s[58:59] offset:576 nt
	global_load_dwordx4 v[84:87], v182, s[58:59] offset:512 nt
	global_load_dwordx4 v[80:83], v182, s[58:59] offset:576 nt
	v_permlane16_swap_b32_e32 v76, v72
	v_permlane16_swap_b32_e32 v77, v73
	v_permlane16_swap_b32_e32 v78, v74
	v_permlane16_swap_b32_e32 v79, v75
	v_permlane32_swap_b32_e32 v76, v72
	v_permlane32_swap_b32_e32 v77, v73
	v_permlane32_swap_b32_e32 v78, v74
	v_permlane32_swap_b32_e32 v79, v75
	s_nop 1
	s_waitcnt vmcnt(26)
	v_pk_add_f32 v[162:163], v[78:79], v[162:163]
	v_pk_add_f32 v[160:161], v[76:77], v[160:161]
	v_pk_add_f32 v[166:167], v[74:75], v[166:167]
	v_pk_add_f32 v[164:165], v[72:73], v[164:165]
	global_store_dwordx4 v179, v[160:163], s[58:59] nt
	global_store_dwordx4 v179, v[164:167], s[58:59] offset:64 nt
	global_load_dwordx4 v[76:79], v183, s[58:59] nt
	global_load_dwordx4 v[72:75], v183, s[58:59] offset:64 nt
	v_permlane16_swap_b32_e32 v68, v64
	v_permlane16_swap_b32_e32 v69, v65
	v_permlane16_swap_b32_e32 v70, v66
	v_permlane16_swap_b32_e32 v71, v67
	v_permlane32_swap_b32_e32 v68, v64
	v_permlane32_swap_b32_e32 v69, v65
	v_permlane32_swap_b32_e32 v70, v66
	v_permlane32_swap_b32_e32 v71, v67
	s_nop 1
	s_waitcnt vmcnt(28)
	v_pk_add_f32 v[170:171], v[70:71], v[170:171]
	v_pk_add_f32 v[168:169], v[68:69], v[168:169]
	v_pk_add_f32 v[130:131], v[66:67], v[130:131]
	v_pk_add_f32 v[128:129], v[64:65], v[128:129]
	global_store_dwordx4 v179, v[168:171], s[58:59] offset:512 nt
	global_store_dwordx4 v179, v[128:131], s[58:59] offset:576 nt
	global_load_dwordx4 v[68:71], v183, s[58:59] offset:512 nt
	global_load_dwordx4 v[64:67], v183, s[58:59] offset:576 nt
	v_permlane16_swap_b32_e32 v60, v56
	v_permlane16_swap_b32_e32 v61, v57
	v_permlane16_swap_b32_e32 v62, v58
	v_permlane16_swap_b32_e32 v63, v59
	v_permlane32_swap_b32_e32 v60, v56
	v_permlane32_swap_b32_e32 v61, v57
	v_permlane32_swap_b32_e32 v62, v58
	v_permlane32_swap_b32_e32 v63, v59
	s_nop 1
	s_waitcnt vmcnt(28)
	v_pk_add_f32 v[126:127], v[62:63], v[126:127]
	v_pk_add_f32 v[124:125], v[60:61], v[124:125]
	v_pk_add_f32 v[122:123], v[58:59], v[122:123]
	v_pk_add_f32 v[120:121], v[56:57], v[120:121]
	global_store_dwordx4 v180, v[124:127], s[58:59] nt
	global_store_dwordx4 v180, v[120:123], s[58:59] offset:64 nt
	v_permlane16_swap_b32_e32 v52, v48
	v_permlane16_swap_b32_e32 v53, v49
	v_permlane16_swap_b32_e32 v54, v50
	v_permlane16_swap_b32_e32 v55, v51
	v_permlane32_swap_b32_e32 v52, v48
	v_permlane32_swap_b32_e32 v53, v49
	v_permlane32_swap_b32_e32 v54, v50
	v_permlane32_swap_b32_e32 v55, v51
	s_nop 1
	s_waitcnt vmcnt(26)
	v_pk_add_f32 v[118:119], v[54:55], v[118:119]
	v_pk_add_f32 v[116:117], v[52:53], v[116:117]
	v_pk_add_f32 v[114:115], v[50:51], v[114:115]
	v_pk_add_f32 v[112:113], v[48:49], v[112:113]
	global_store_dwordx4 v180, v[116:119], s[58:59] offset:512 nt
	global_store_dwordx4 v180, v[112:115], s[58:59] offset:576 nt
	v_permlane16_swap_b32_e32 v44, v40
	v_permlane16_swap_b32_e32 v45, v41
	v_permlane16_swap_b32_e32 v46, v42
	v_permlane16_swap_b32_e32 v47, v43
	v_permlane32_swap_b32_e32 v44, v40
	v_permlane32_swap_b32_e32 v45, v41
	v_permlane32_swap_b32_e32 v46, v42
	v_permlane32_swap_b32_e32 v47, v43
	s_nop 1
	s_waitcnt vmcnt(24)
	v_pk_add_f32 v[110:111], v[46:47], v[110:111]
	v_pk_add_f32 v[108:109], v[44:45], v[108:109]
	v_pk_add_f32 v[106:107], v[42:43], v[106:107]
	v_pk_add_f32 v[104:105], v[40:41], v[104:105]
	global_store_dwordx4 v181, v[108:111], s[58:59] nt
	global_store_dwordx4 v181, v[104:107], s[58:59] offset:64 nt
	v_permlane16_swap_b32_e32 v36, v32
	v_permlane16_swap_b32_e32 v37, v33
	v_permlane16_swap_b32_e32 v38, v34
	v_permlane16_swap_b32_e32 v39, v35
	v_permlane32_swap_b32_e32 v36, v32
	v_permlane32_swap_b32_e32 v37, v33
	v_permlane32_swap_b32_e32 v38, v34
	v_permlane32_swap_b32_e32 v39, v35
	s_nop 1
	s_waitcnt vmcnt(22)
	v_pk_add_f32 v[102:103], v[38:39], v[102:103]
	v_pk_add_f32 v[100:101], v[36:37], v[100:101]
	v_pk_add_f32 v[98:99], v[34:35], v[98:99]
	v_pk_add_f32 v[96:97], v[32:33], v[96:97]
	global_store_dwordx4 v181, v[100:103], s[58:59] offset:512 nt
	global_store_dwordx4 v181, v[96:99], s[58:59] offset:576 nt
	v_permlane16_swap_b32_e32 v28, v24
	v_permlane16_swap_b32_e32 v29, v25
	v_permlane16_swap_b32_e32 v30, v26
	v_permlane16_swap_b32_e32 v31, v27
	v_permlane32_swap_b32_e32 v28, v24
	v_permlane32_swap_b32_e32 v29, v25
	v_permlane32_swap_b32_e32 v30, v26
	v_permlane32_swap_b32_e32 v31, v27
	s_nop 1
	s_waitcnt vmcnt(20)
	v_pk_add_f32 v[94:95], v[30:31], v[94:95]
	v_pk_add_f32 v[92:93], v[28:29], v[92:93]
	v_pk_add_f32 v[90:91], v[26:27], v[90:91]
	v_pk_add_f32 v[88:89], v[24:25], v[88:89]
	global_store_dwordx4 v182, v[92:95], s[58:59] nt
	global_store_dwordx4 v182, v[88:91], s[58:59] offset:64 nt
	v_permlane16_swap_b32_e32 v20, v16
	v_permlane16_swap_b32_e32 v21, v17
	v_permlane16_swap_b32_e32 v22, v18
	v_permlane16_swap_b32_e32 v23, v19
	v_permlane32_swap_b32_e32 v20, v16
	v_permlane32_swap_b32_e32 v21, v17
	v_permlane32_swap_b32_e32 v22, v18
	v_permlane32_swap_b32_e32 v23, v19
	s_nop 1
	s_waitcnt vmcnt(18)
	v_pk_add_f32 v[86:87], v[22:23], v[86:87]
	v_pk_add_f32 v[84:85], v[20:21], v[84:85]
	v_pk_add_f32 v[82:83], v[18:19], v[82:83]
	v_pk_add_f32 v[80:81], v[16:17], v[80:81]
	global_store_dwordx4 v182, v[84:87], s[58:59] offset:512 nt
	global_store_dwordx4 v182, v[80:83], s[58:59] offset:576 nt
	v_permlane16_swap_b32_e32 v12, v8
	v_permlane16_swap_b32_e32 v13, v9
	v_permlane16_swap_b32_e32 v14, v10
	v_permlane16_swap_b32_e32 v15, v11
	v_permlane32_swap_b32_e32 v12, v8
	v_permlane32_swap_b32_e32 v13, v9
	v_permlane32_swap_b32_e32 v14, v10
	v_permlane32_swap_b32_e32 v15, v11
	s_nop 1
	s_waitcnt vmcnt(16)
	v_pk_add_f32 v[78:79], v[14:15], v[78:79]
	v_pk_add_f32 v[76:77], v[12:13], v[76:77]
	v_pk_add_f32 v[74:75], v[10:11], v[74:75]
	v_pk_add_f32 v[72:73], v[8:9], v[72:73]
	global_store_dwordx4 v183, v[76:79], s[58:59] nt
	global_store_dwordx4 v183, v[72:75], s[58:59] offset:64 nt
	v_permlane16_swap_b32_e32 v4, v0
	v_permlane16_swap_b32_e32 v5, v1
	v_permlane16_swap_b32_e32 v6, v2
	v_permlane16_swap_b32_e32 v7, v3
	v_permlane32_swap_b32_e32 v4, v0
	v_permlane32_swap_b32_e32 v5, v1
	v_permlane32_swap_b32_e32 v6, v2
	v_permlane32_swap_b32_e32 v7, v3
	s_nop 1
	s_waitcnt vmcnt(14)
	v_pk_add_f32 v[70:71], v[6:7], v[70:71]
	v_pk_add_f32 v[68:69], v[4:5], v[68:69]
	v_pk_add_f32 v[66:67], v[2:3], v[66:67]
	v_pk_add_f32 v[64:65], v[0:1], v[64:65]
	global_store_dwordx4 v183, v[68:71], s[58:59] offset:512 nt
	global_store_dwordx4 v183, v[64:67], s[58:59] offset:576 nt
	s_branch .LBB0_567
